# speedup vs baseline: 1.0940x; 1.0241x over previous
; #define SCAN_BAR() do { asm volatile("s_waitcnt lgkmcnt(0)" ::: "memory"); __builtin_amdgcn_s_barrier(); asm volatile("" ::: "memory"); } while (0)
; __device__ __forceinline__ void scan_phase(const ScanArgs& s, char* shm) {
;     ...
;       if (par == 0) { LOADRAW(0); PROC(0, 0); PROC(1, 0); LOADRAW(2); } else { LOADRAW(1); PROC(0, 1); }
;       SCAN_BAR();
;       for (int c = 0; c < NCH + 2; ++c) {
;         if ((c & 1) == par) { if (c + 2 < NCH) PROC(0, c + 2); }
;         else if (c + 1 < NCH) { PROC(1, c + 1); if (c + 3 < NCH) LOADRAW(c + 3); }
.LBB0_139:
	s_lshr_b32 s68, s38, 6
	s_add_i32 s67, s67, s68
	s_and_b32 s67, s67, 15
	s_lshl_b64 s[60:61], s[62:63], 25
	s_lshl_b32 s67, s67, 7
	s_or_b32 s60, s60, s67
	s_lshl_b32 s67, s38, 1
	s_waitcnt lgkmcnt(0)
	s_barrier
	s_and_b32 s67, s67, 0x70
	v_lshl_add_u64 v[142:143], v[136:137], 0, s[60:61]
	s_or_b32 s60, s60, s67
	v_lshl_add_u64 v[144:145], v[138:139], 0, s[60:61]
	s_mov_b32 s67, 0
	s_mov_b64 s[80:81], 0
	s_mov_b32 s68, 32
	s_waitcnt vmcnt(0)
	s_branch .LBB0_143
.LBB0_143:
	s_and_b32 s60, s67, 1
	s_cmp_lg_u32 s60, s66
	s_cbranch_scc0 .Lp_proc0
	s_cmpk_gt_u32 s67, 0x3fc
	s_cbranch_scc1 .Lp_nolr0
	v_lshl_add_u64 v[112:113], v[142:143], 0, s[80:81]
	v_lshl_add_u64 v[116:117], v[144:145], 0, s[80:81]
	v_add_co_u32_e32 v72, vcc, 0x3a18000, v112
	s_nop 1
	v_addc_co_u32_e32 v73, vcc, 0, v113, vcc
	v_add_co_u32_e32 v84, vcc, 0x7a18000, v112
	s_nop 1
	v_addc_co_u32_e32 v85, vcc, 0, v113, vcc
	v_add_co_u32_e32 v80, vcc, 0x17a18000, v112
	global_load_dwordx4 v[24:27], v[72:73], off
	global_load_dwordx4 v[28:31], v[84:85], off
	v_addc_co_u32_e32 v81, vcc, 0, v113, vcc
	global_load_dwordx4 v[32:35], v[80:81], off
	global_load_dwordx4 v[36:39], v[84:85], off offset:2048
	v_add_co_u32_e32 v86, vcc, 0xfa18000, v112
	s_nop 1
	v_addc_co_u32_e32 v87, vcc, 0, v113, vcc
	global_load_dwordx4 v[40:43], v[86:87], off
	v_add_co_u32_e32 v88, vcc, 0x18000, v116
	s_nop 1
	v_addc_co_u32_e32 v89, vcc, 0, v117, vcc
	global_load_dwordx4 v[48:51], v[88:89], off
	s_waitcnt vmcnt(6)
	s_branch .Lp_proc1
.Lp_nolr0:
	s_waitcnt vmcnt(0)
	s_cmpk_gt_u32 s67, 0x3fe
	s_cbranch_scc1 .Lp_join
.Lp_proc1:
	v_cvt_f32_f16_e32 v72, v64
	v_cvt_f32_f16_sdwa v73, v64 dst_sel:DWORD dst_unused:UNUSED_PAD src0_sel:WORD_1
	v_cvt_f32_f16_e32 v76, v65
	v_cvt_f32_f16_sdwa v77, v65 dst_sel:DWORD dst_unused:UNUSED_PAD src0_sel:WORD_1
	v_cvt_f32_f16_e32 v78, v66
	v_mul_f32_e32 v72, 0xbfb8aa3b, v72
	v_cvt_f32_f16_sdwa v79, v66 dst_sel:DWORD dst_unused:UNUSED_PAD src0_sel:WORD_1
	v_exp_f32_e32 v74, v72
	v_mul_f32_e32 v72, 0xbfb8aa3b, v73
	v_cvt_f32_f16_e32 v90, v67
	v_exp_f32_e32 v75, v72
	v_mul_f32_e32 v72, 0xbfb8aa3b, v76
	v_exp_f32_e32 v76, v72
	v_mul_f32_e32 v72, 0xbfb8aa3b, v77
	v_exp_f32_e32 v77, v72
	v_mul_f32_e32 v72, 0xbfb8aa3b, v78
	v_exp_f32_e32 v88, v72
	v_mul_f32_e32 v72, 0xbfb8aa3b, v79
	v_exp_f32_e32 v89, v72
	v_mul_f32_e32 v72, 0xbfb8aa3b, v90
	v_exp_f32_e32 v90, v72
	v_lshlrev_b32_e32 v72, 16, v60
	v_and_b32_e32 v73, 0xffff0000, v60
	v_pk_mul_f32 v[78:79], v[12:13], v[72:73]
	v_lshlrev_b32_e32 v92, 16, v61
	v_and_b32_e32 v93, 0xffff0000, v61
	v_pk_mul_f32 v[72:73], v[78:79], v[78:79]
	v_pk_mul_f32 v[100:101], v[14:15], v[92:93]
	v_lshlrev_b32_e32 v94, 16, v62
	v_pk_mul_f32 v[92:93], v[100:101], v[100:101]
	v_and_b32_e32 v95, 0xffff0000, v62
	v_add_f32_e32 v72, v72, v73
	v_pk_mul_f32 v[102:103], v[8:9], v[94:95]
	v_add_f32_e32 v72, v72, v92
	v_pk_mul_f32 v[94:95], v[102:103], v[102:103]
	v_lshlrev_b32_e32 v96, 16, v63
	v_and_b32_e32 v97, 0xffff0000, v63
	v_add_f32_e32 v72, v93, v72
	v_pk_mul_f32 v[104:105], v[10:11], v[96:97]
	v_add_f32_e32 v72, v94, v72
	v_pk_mul_f32 v[96:97], v[104:105], v[104:105]
	v_add_f32_e32 v72, v95, v72
	v_add_f32_e32 v72, v96, v72
	v_add_f32_e32 v72, v97, v72
	v_cvt_f32_f16_sdwa v91, v67 dst_sel:DWORD dst_unused:UNUSED_PAD src0_sel:WORD_1
	s_add_i32 s60, s67, 1
	v_add_f32_dpp v72, v72, v72 quad_perm:[1,0,3,2] row_mask:0xf bank_mask:0xf bound_ctrl:1
	s_and_b32 s60, s60, 3
	s_mul_i32 s61, s60, 0x4400
	v_add_f32_dpp v72, v72, v72 quad_perm:[2,3,0,1] row_mask:0xf bank_mask:0xf bound_ctrl:1
	v_mul_f32_e32 v91, 0xbfb8aa3b, v91
	v_add_u32_e32 v73, s61, v153
	v_add_f32_dpp v72, v72, v72 row_half_mirror row_mask:0xf bank_mask:0xf bound_ctrl:1
	v_rsq_f32_e32 v72, v72
	v_exp_f32_e32 v91, v91
	v_lshl_add_u32 v116, v147, 2, v73
	v_lshlrev_b32_e32 v106, 16, v57
	v_min_f32_e32 v72, 0x5368d4a5, v72
	v_pk_mul_f32 v[92:93], v[72:73], v[78:79] op_sel_hi:[0,1] neg_lo:[0,1] neg_hi:[0,1]
	v_pk_mul_f32 v[94:95], v[72:73], v[100:101] op_sel_hi:[0,1] neg_lo:[0,1] neg_hi:[0,1]
	v_pk_mul_f32 v[96:97], v[72:73], v[102:103] op_sel_hi:[0,1] neg_lo:[0,1] neg_hi:[0,1]
	v_pk_mul_f32 v[98:99], v[72:73], v[104:105] op_sel_hi:[0,1] neg_lo:[0,1] neg_hi:[0,1]
	ds_write_b128 v116, v[92:95]
	ds_write_b128 v116, v[96:99] offset:16
	ds_write_b128 v116, v[74:77] offset:256
	ds_write_b128 v116, v[88:91] offset:272
	v_lshlrev_b32_e32 v96, 16, v52
	v_and_b32_e32 v97, 0xffff0000, v52
	v_lshlrev_b32_e32 v98, 16, v56
	v_and_b32_e32 v99, 0xffff0000, v56
	v_pk_mul_f32 v[76:77], v[12:13], v[96:97]
	v_and_b32_e32 v107, 0xffff0000, v57
	v_pk_mul_f32 v[88:89], v[76:77], v[98:99]
	v_pk_mul_f32 v[74:75], v[76:77], v[76:77]
	v_pk_mul_f32 v[78:79], v[78:79], v[88:89]
	v_lshlrev_b32_e32 v108, 16, v58
	v_add_f32_e32 v78, 0, v78
	v_add_f32_e32 v94, v79, v78
	v_lshlrev_b32_e32 v78, 16, v53
	v_and_b32_e32 v79, 0xffff0000, v53
	v_pk_mul_f32 v[90:91], v[14:15], v[78:79]
	v_and_b32_e32 v109, 0xffff0000, v58
	v_pk_mul_f32 v[88:89], v[90:91], v[106:107]
	v_pk_mul_f32 v[92:93], v[90:91], v[90:91]
	v_pk_mul_f32 v[88:89], v[100:101], v[88:89]
	v_lshlrev_b32_e32 v100, 16, v54
	v_and_b32_e32 v101, 0xffff0000, v54
	v_add_f32_e32 v88, v88, v94
	v_pk_mul_f32 v[94:95], v[8:9], v[100:101]
	v_add_f32_e32 v74, v74, v75
	v_add_f32_e32 v112, v89, v88
	v_pk_mul_f32 v[88:89], v[94:95], v[108:109]
	v_add_f32_e32 v74, v74, v92
	v_pk_mul_f32 v[110:111], v[94:95], v[94:95]
	v_pk_mul_f32 v[88:89], v[102:103], v[88:89]
	v_lshlrev_b32_e32 v102, 16, v55
	v_and_b32_e32 v103, 0xffff0000, v55
	v_add_f32_e32 v74, v93, v74
	v_add_f32_e32 v88, v88, v112
	v_pk_mul_f32 v[114:115], v[10:11], v[102:103]
	v_add_f32_e32 v74, v110, v74
; #define SCAN_BAR() do { asm volatile("s_waitcnt lgkmcnt(0)" ::: "memory"); __builtin_amdgcn_s_barrier(); asm volatile("" ::: "memory"); } while (0)
; __device__ __forceinline__ void scan_phase(const ScanArgs& s, char* shm) {
;     ...
;       if (par == 0) { LOADRAW(0); PROC(0, 0); PROC(1, 0); LOADRAW(2); } else { LOADRAW(1); PROC(0, 1); }
;       SCAN_BAR();
;       for (int c = 0; c < NCH + 2; ++c) {
;         if ((c & 1) == par) { if (c + 2 < NCH) PROC(0, c + 2); }
;         else if (c + 1 < NCH) { PROC(1, c + 1); if (c + 3 < NCH) LOADRAW(c + 3); }
	v_add_f32_e32 v117, v89, v88
	v_pk_mul_f32 v[88:89], v[114:115], v[114:115]
	v_add_f32_e32 v74, v111, v74
	v_add_f32_e32 v74, v88, v74
	v_add_f32_e32 v74, v89, v74
	v_lshlrev_b32_e32 v112, 16, v59
	v_and_b32_e32 v113, 0xffff0000, v59
	v_add_f32_dpp v74, v74, v74 quad_perm:[1,0,3,2] row_mask:0xf bank_mask:0xf bound_ctrl:1
	v_lshlrev_b32_e32 v80, 16, v44
	v_and_b32_e32 v81, 0xffff0000, v44
	v_add_f32_dpp v74, v74, v74 quad_perm:[2,3,0,1] row_mask:0xf bank_mask:0xf bound_ctrl:1
	v_lshlrev_b32_e32 v82, 16, v45
	v_and_b32_e32 v83, 0xffff0000, v45
	v_add_f32_dpp v74, v74, v74 row_half_mirror row_mask:0xf bank_mask:0xf bound_ctrl:1
	v_rsq_f32_e32 v88, v74
	v_pk_mul_f32 v[74:75], v[114:115], v[112:113]
	v_lshlrev_b32_e32 v84, 16, v46
	v_pk_mul_f32 v[104:105], v[104:105], v[74:75]
	v_min_f32_e32 v74, 0x5368d4a5, v88
	v_pk_mul_f32 v[76:77], v[76:77], v[74:75] op_sel_hi:[1,0]
	v_and_b32_e32 v85, 0xffff0000, v46
	v_pk_mul_f32 v[88:89], v[76:77], v[98:99]
	v_pk_mul_f32 v[76:77], v[90:91], v[74:75] op_sel_hi:[1,0]
	v_lshlrev_b32_e32 v86, 16, v47
	v_pk_mul_f32 v[90:91], v[76:77], v[106:107]
	v_pk_mul_f32 v[76:77], v[94:95], v[74:75] op_sel_hi:[1,0]
	v_and_b32_e32 v87, 0xffff0000, v47
	v_pk_mul_f32 v[92:93], v[76:77], v[108:109]
	v_pk_mul_f32 v[76:77], v[114:115], v[74:75] op_sel_hi:[1,0]
	v_add_f32_e32 v75, v104, v117
	v_pk_mul_f32 v[94:95], v[76:77], v[112:113]
	ds_write_b128 v116, v[88:91] offset:512
	ds_write_b128 v116, v[92:95] offset:528
	v_pk_add_f32 v[88:89], v[98:99], -1.0 op_sel_hi:[1,0]
	v_add_f32_e32 v75, v105, v75
	v_pk_fma_f32 v[88:89], v[20:21], v[88:89], 1.0 op_sel_hi:[1,1,0]
	s_nop 0
	v_pk_mul_f32 v[88:89], v[88:89], v[96:97]
	v_add_f32_dpp v75, v75, v75 quad_perm:[1,0,3,2] row_mask:0xf bank_mask:0xf bound_ctrl:1
	v_mul_f32_e32 v77, v88, v80
	v_fma_f32 v77, v0, v77, 0
	v_mul_f32_e32 v90, v89, v81
	v_fmac_f32_e32 v77, v1, v90
	v_pk_add_f32 v[90:91], v[106:107], -1.0 op_sel_hi:[1,0]
	v_add_f32_dpp v75, v75, v75 quad_perm:[2,3,0,1] row_mask:0xf bank_mask:0xf bound_ctrl:1
	v_pk_fma_f32 v[90:91], v[22:23], v[90:91], 1.0 op_sel_hi:[1,1,0]
	s_nop 0
	v_pk_mul_f32 v[90:91], v[90:91], v[78:79]
	ds_write_b128 v116, v[88:91] offset:768
	v_mul_f32_e32 v78, v90, v82
	v_mul_f32_e32 v79, v91, v83
	v_fmac_f32_e32 v77, v2, v78
	v_fmac_f32_e32 v77, v3, v79
	v_pk_add_f32 v[78:79], v[108:109], -1.0 op_sel_hi:[1,0]
	v_mov_b32_dpp v76, v75 row_half_mirror row_mask:0xf bank_mask:0xf bound_ctrl:1
	v_pk_fma_f32 v[78:79], v[16:17], v[78:79], 1.0 op_sel_hi:[1,1,0]
	s_nop 0
	v_pk_mul_f32 v[88:89], v[78:79], v[100:101]
	s_nop 0
	v_mul_f32_e32 v78, v88, v84
	v_mul_f32_e32 v79, v89, v85
	v_fmac_f32_e32 v77, v4, v78
	v_fmac_f32_e32 v77, v5, v79
	v_pk_add_f32 v[78:79], v[112:113], -1.0 op_sel_hi:[1,0]
	s_nop 0
	v_pk_fma_f32 v[78:79], v[18:19], v[78:79], 1.0 op_sel_hi:[1,1,0]
	s_nop 0
	v_pk_mul_f32 v[90:91], v[78:79], v[102:103]
	ds_write_b128 v116, v[88:91] offset:784
	v_mul_f32_e32 v78, v90, v86
	v_mul_f32_e32 v79, v91, v87
	v_fmac_f32_e32 v77, v6, v78
	v_fmac_f32_e32 v77, v7, v79
	v_lshl_add_u32 v79, s60, 12, v155
	ds_write_b128 v79, v[80:83]
	ds_write_b128 v79, v[84:87] offset:16
	v_add_f32_dpp v77, v77, v77 quad_perm:[1,0,3,2] row_mask:0xf bank_mask:0xf bound_ctrl:1
	s_nop 1
	v_add_f32_dpp v77, v77, v77 quad_perm:[2,3,0,1] row_mask:0xf bank_mask:0xf bound_ctrl:1
	s_nop 1
	v_mov_b32_dpp v78, v77 row_half_mirror row_mask:0xf bank_mask:0xf bound_ctrl:1
	s_and_saveexec_b64 s[60:61], s[8:9]
	s_cbranch_execz .LBB0_147
	v_add_f32_e32 v75, v75, v76
	v_mul_f32_e64 v74, v74, -v75
	v_mul_f32_e32 v75, v74, v72
	v_add_f32_e32 v78, v77, v78
	v_lshlrev_b32_e32 v74, 16, v68
	v_and_b32_e32 v76, 0xffff0000, v68
	v_mov_b32_e32 v77, v75
	ds_write_b128 v73, v[74:77] offset:1024
	v_lshlrev_b32_e32 v74, 16, v69
	v_and_b32_e32 v76, 0xffff0000, v69
	s_add_i32 s69, s68, -16
	ds_write_b128 v73, v[74:77] offset:1040
	v_lshlrev_b32_e32 v74, 16, v70
	v_and_b32_e32 v76, 0xffff0000, v70
	s_and_b32 s69, s69, 0x70
	ds_write_b128 v73, v[74:77] offset:1056
	v_lshlrev_b32_e32 v74, 16, v71
	v_and_b32_e32 v76, 0xffff0000, v71
	v_lshl_add_u32 v72, s69, 2, v156
	ds_write_b128 v73, v[74:77] offset:1072
	ds_write_b32 v72, v78
.LBB0_147:
	s_or_b64 exec, exec, s[60:61]
	s_cmpk_gt_u32 s67, 0x3fc
	s_cbranch_scc1 .Lp_join
	v_lshl_add_u64 v[112:113], v[142:143], 0, s[80:81]
	v_lshl_add_u64 v[116:117], v[144:145], 0, s[80:81]
	v_add_u32_e32 v106, s80, v130
	s_mov_b32 s60, 0x7a1c000
	v_add_co_u32_e32 v84, vcc, 0x3a1c000, v112
	s_nop 1
	v_addc_co_u32_e32 v85, vcc, 0, v113, vcc
	v_add_co_u32_e32 v96, vcc, 0x7a1c000, v112
	s_nop 1
	v_addc_co_u32_e32 v97, vcc, 0, v113, vcc
	v_add_co_u32_e32 v104, vcc, 0x17a1c000, v112
	global_load_dwordx4 v[44:47], v[84:85], off
	global_load_dwordx4 v[52:55], v[96:97], off
	v_addc_co_u32_e32 v105, vcc, 0, v113, vcc
	v_cmp_eq_u32_e32 vcc, 0, v106
	s_nop 1
	v_cndmask_b32_e64 v132, v166, 0, vcc
	v_lshl_add_u64 v[106:107], s[80:81], 0, v[132:133]
	v_lshl_add_u64 v[106:107], v[142:143], 0, v[106:107]
	v_add_co_u32_e32 v108, vcc, s60, v106
	s_nop 1
	v_addc_co_u32_e32 v109, vcc, 0, v107, vcc
	v_add_co_u32_e32 v112, vcc, 0xfa1c000, v112
	global_load_dwordx4 v[56:59], v[104:105], off
	global_load_dwordx4 v[60:63], v[108:109], off
	v_addc_co_u32_e32 v113, vcc, 0, v113, vcc
	v_add_co_u32_e32 v116, vcc, 0x1c000, v116
	s_nop 1
	v_addc_co_u32_e32 v117, vcc, 0, v117, vcc
	global_load_dwordx4 v[64:67], v[112:113], off
	global_load_dwordx4 v[68:71], v[116:117], off
	s_branch .Lp_join
; __device__ __forceinline__ void scan_phase(const ScanArgs& s, char* shm) {
;     ...
;         if ((c & 1) == par) { if (c + 2 < NCH) PROC(0, c + 2); }
.Lp_proc0:
	s_cmpk_gt_u32 s67, 0x3fd
	s_cbranch_scc1 .Lp_join
	s_waitcnt vmcnt(6)
	v_cvt_f32_f16_e32 v72, v40
	v_cvt_f32_f16_sdwa v73, v40 dst_sel:DWORD dst_unused:UNUSED_PAD src0_sel:WORD_1
	v_cvt_f32_f16_e32 v76, v41
	v_cvt_f32_f16_sdwa v77, v41 dst_sel:DWORD dst_unused:UNUSED_PAD src0_sel:WORD_1
	v_cvt_f32_f16_e32 v78, v42
	v_mul_f32_e32 v72, 0xbfb8aa3b, v72
	v_cvt_f32_f16_sdwa v79, v42 dst_sel:DWORD dst_unused:UNUSED_PAD src0_sel:WORD_1
	v_exp_f32_e32 v74, v72
	v_mul_f32_e32 v72, 0xbfb8aa3b, v73
	v_cvt_f32_f16_e32 v90, v43
	v_exp_f32_e32 v75, v72
	v_mul_f32_e32 v72, 0xbfb8aa3b, v76
	v_exp_f32_e32 v76, v72
	v_mul_f32_e32 v72, 0xbfb8aa3b, v77
	v_exp_f32_e32 v77, v72
	v_mul_f32_e32 v72, 0xbfb8aa3b, v78
	v_exp_f32_e32 v88, v72
	v_mul_f32_e32 v72, 0xbfb8aa3b, v79
	v_exp_f32_e32 v89, v72
	v_mul_f32_e32 v72, 0xbfb8aa3b, v90
	v_exp_f32_e32 v90, v72
	v_lshlrev_b32_e32 v72, 16, v36
	v_and_b32_e32 v73, 0xffff0000, v36
	v_pk_mul_f32 v[78:79], v[12:13], v[72:73]
	v_lshlrev_b32_e32 v92, 16, v37
	v_and_b32_e32 v93, 0xffff0000, v37
	v_pk_mul_f32 v[72:73], v[78:79], v[78:79]
	v_pk_mul_f32 v[100:101], v[14:15], v[92:93]
	v_lshlrev_b32_e32 v94, 16, v38
	v_pk_mul_f32 v[92:93], v[100:101], v[100:101]
	v_and_b32_e32 v95, 0xffff0000, v38
	v_add_f32_e32 v72, v72, v73
	v_pk_mul_f32 v[102:103], v[8:9], v[94:95]
	v_add_f32_e32 v72, v72, v92
	v_pk_mul_f32 v[94:95], v[102:103], v[102:103]
	v_lshlrev_b32_e32 v96, 16, v39
	v_and_b32_e32 v97, 0xffff0000, v39
	v_add_f32_e32 v72, v93, v72
	v_pk_mul_f32 v[104:105], v[10:11], v[96:97]
	v_add_f32_e32 v72, v94, v72
	v_pk_mul_f32 v[96:97], v[104:105], v[104:105]
	v_add_f32_e32 v72, v95, v72
	v_add_f32_e32 v72, v96, v72
	v_add_f32_e32 v72, v97, v72
	v_cvt_f32_f16_sdwa v91, v43 dst_sel:DWORD dst_unused:UNUSED_PAD src0_sel:WORD_1
	s_add_i32 s60, s67, 2
	v_add_f32_dpp v72, v72, v72 quad_perm:[1,0,3,2] row_mask:0xf bank_mask:0xf bound_ctrl:1
	s_and_b32 s60, s60, 3
	s_mul_i32 s61, s60, 0x4400
	v_add_f32_dpp v72, v72, v72 quad_perm:[2,3,0,1] row_mask:0xf bank_mask:0xf bound_ctrl:1
	v_mul_f32_e32 v91, 0xbfb8aa3b, v91
	v_add_u32_e32 v73, s61, v148
	v_add_f32_dpp v72, v72, v72 row_half_mirror row_mask:0xf bank_mask:0xf bound_ctrl:1
	v_rsq_f32_e32 v72, v72
	v_exp_f32_e32 v91, v91
	v_lshl_add_u32 v116, v147, 2, v73
	v_lshlrev_b32_e32 v106, 16, v33
	v_min_f32_e32 v72, 0x5368d4a5, v72
	v_pk_mul_f32 v[92:93], v[72:73], v[78:79] op_sel_hi:[0,1] neg_lo:[0,1] neg_hi:[0,1]
	v_pk_mul_f32 v[94:95], v[72:73], v[100:101] op_sel_hi:[0,1] neg_lo:[0,1] neg_hi:[0,1]
	v_pk_mul_f32 v[96:97], v[72:73], v[102:103] op_sel_hi:[0,1] neg_lo:[0,1] neg_hi:[0,1]
	v_pk_mul_f32 v[98:99], v[72:73], v[104:105] op_sel_hi:[0,1] neg_lo:[0,1] neg_hi:[0,1]
	ds_write_b128 v116, v[92:95]
	ds_write_b128 v116, v[96:99] offset:16
	ds_write_b128 v116, v[74:77] offset:256
	ds_write_b128 v116, v[88:91] offset:272
	v_lshlrev_b32_e32 v96, 16, v28
	v_and_b32_e32 v97, 0xffff0000, v28
	v_lshlrev_b32_e32 v98, 16, v32
	v_and_b32_e32 v99, 0xffff0000, v32
	v_pk_mul_f32 v[76:77], v[12:13], v[96:97]
	v_and_b32_e32 v107, 0xffff0000, v33
	v_pk_mul_f32 v[88:89], v[76:77], v[98:99]
	v_pk_mul_f32 v[74:75], v[76:77], v[76:77]
	v_pk_mul_f32 v[78:79], v[78:79], v[88:89]
	v_lshlrev_b32_e32 v108, 16, v34
	v_add_f32_e32 v78, 0, v78
	v_add_f32_e32 v94, v79, v78
	v_lshlrev_b32_e32 v78, 16, v29
	v_and_b32_e32 v79, 0xffff0000, v29
	v_pk_mul_f32 v[90:91], v[14:15], v[78:79]
	v_and_b32_e32 v109, 0xffff0000, v34
	v_pk_mul_f32 v[88:89], v[90:91], v[106:107]
	v_pk_mul_f32 v[92:93], v[90:91], v[90:91]
	v_pk_mul_f32 v[88:89], v[100:101], v[88:89]
	v_lshlrev_b32_e32 v100, 16, v30
	v_and_b32_e32 v101, 0xffff0000, v30
	v_add_f32_e32 v88, v88, v94
	v_pk_mul_f32 v[94:95], v[8:9], v[100:101]
	v_add_f32_e32 v74, v74, v75
	v_add_f32_e32 v112, v89, v88
	v_pk_mul_f32 v[88:89], v[94:95], v[108:109]
	v_add_f32_e32 v74, v74, v92
	v_pk_mul_f32 v[110:111], v[94:95], v[94:95]
	v_pk_mul_f32 v[88:89], v[102:103], v[88:89]
	v_lshlrev_b32_e32 v102, 16, v31
	v_and_b32_e32 v103, 0xffff0000, v31
	v_add_f32_e32 v74, v93, v74
	v_add_f32_e32 v88, v88, v112
	v_pk_mul_f32 v[114:115], v[10:11], v[102:103]
	v_add_f32_e32 v74, v110, v74
	v_add_f32_e32 v117, v89, v88
	v_pk_mul_f32 v[88:89], v[114:115], v[114:115]
	v_add_f32_e32 v74, v111, v74
	v_add_f32_e32 v74, v88, v74
	v_add_f32_e32 v74, v89, v74
	v_lshlrev_b32_e32 v112, 16, v35
	v_and_b32_e32 v113, 0xffff0000, v35
	v_add_f32_dpp v74, v74, v74 quad_perm:[1,0,3,2] row_mask:0xf bank_mask:0xf bound_ctrl:1
	v_lshlrev_b32_e32 v80, 16, v24
	v_and_b32_e32 v81, 0xffff0000, v24
	v_add_f32_dpp v74, v74, v74 quad_perm:[2,3,0,1] row_mask:0xf bank_mask:0xf bound_ctrl:1
	v_lshlrev_b32_e32 v82, 16, v25
	v_and_b32_e32 v83, 0xffff0000, v25
	v_add_f32_dpp v74, v74, v74 row_half_mirror row_mask:0xf bank_mask:0xf bound_ctrl:1
	v_rsq_f32_e32 v88, v74
	v_pk_mul_f32 v[74:75], v[114:115], v[112:113]
	v_lshlrev_b32_e32 v84, 16, v26
	v_pk_mul_f32 v[104:105], v[104:105], v[74:75]
	v_min_f32_e32 v74, 0x5368d4a5, v88
	v_pk_mul_f32 v[76:77], v[76:77], v[74:75] op_sel_hi:[1,0]
	v_and_b32_e32 v85, 0xffff0000, v26
	v_pk_mul_f32 v[88:89], v[76:77], v[98:99]
	v_pk_mul_f32 v[76:77], v[90:91], v[74:75] op_sel_hi:[1,0]
	v_lshlrev_b32_e32 v86, 16, v27
	v_pk_mul_f32 v[90:91], v[76:77], v[106:107]
	v_pk_mul_f32 v[76:77], v[94:95], v[74:75] op_sel_hi:[1,0]
	v_and_b32_e32 v87, 0xffff0000, v27
	v_pk_mul_f32 v[92:93], v[76:77], v[108:109]
	v_pk_mul_f32 v[76:77], v[114:115], v[74:75] op_sel_hi:[1,0]
	v_add_f32_e32 v75, v104, v117
	v_pk_mul_f32 v[94:95], v[76:77], v[112:113]
	ds_write_b128 v116, v[88:91] offset:512
	ds_write_b128 v116, v[92:95] offset:528
	v_pk_add_f32 v[88:89], v[98:99], -1.0 op_sel_hi:[1,0]
	v_add_f32_e32 v75, v105, v75
	v_pk_fma_f32 v[88:89], v[20:21], v[88:89], 1.0 op_sel_hi:[1,1,0]
	s_nop 0
	v_pk_mul_f32 v[88:89], v[88:89], v[96:97]
	v_add_f32_dpp v75, v75, v75 quad_perm:[1,0,3,2] row_mask:0xf bank_mask:0xf bound_ctrl:1
	v_mul_f32_e32 v77, v88, v80
	v_fma_f32 v77, v0, v77, 0
	v_mul_f32_e32 v90, v89, v81
	v_fmac_f32_e32 v77, v1, v90
	v_pk_add_f32 v[90:91], v[106:107], -1.0 op_sel_hi:[1,0]
	v_add_f32_dpp v75, v75, v75 quad_perm:[2,3,0,1] row_mask:0xf bank_mask:0xf bound_ctrl:1
	v_pk_fma_f32 v[90:91], v[22:23], v[90:91], 1.0 op_sel_hi:[1,1,0]
	s_nop 0
	v_pk_mul_f32 v[90:91], v[90:91], v[78:79]
	ds_write_b128 v116, v[88:91] offset:768
	v_mul_f32_e32 v78, v90, v82
	v_mul_f32_e32 v79, v91, v83
	v_fmac_f32_e32 v77, v2, v78
	v_fmac_f32_e32 v77, v3, v79
	v_pk_add_f32 v[78:79], v[108:109], -1.0 op_sel_hi:[1,0]
	v_mov_b32_dpp v76, v75 row_half_mirror row_mask:0xf bank_mask:0xf bound_ctrl:1
	v_pk_fma_f32 v[78:79], v[16:17], v[78:79], 1.0 op_sel_hi:[1,1,0]
	s_nop 0
	v_pk_mul_f32 v[88:89], v[78:79], v[100:101]
	s_nop 0
	v_mul_f32_e32 v78, v88, v84
	v_mul_f32_e32 v79, v89, v85
	v_fmac_f32_e32 v77, v4, v78
	v_fmac_f32_e32 v77, v5, v79
	v_pk_add_f32 v[78:79], v[112:113], -1.0 op_sel_hi:[1,0]
	s_nop 0
	v_pk_fma_f32 v[78:79], v[18:19], v[78:79], 1.0 op_sel_hi:[1,1,0]
	s_nop 0
	v_pk_mul_f32 v[90:91], v[78:79], v[102:103]
	ds_write_b128 v116, v[88:91] offset:784
	v_mul_f32_e32 v78, v90, v86
	v_mul_f32_e32 v79, v91, v87
	v_fmac_f32_e32 v77, v6, v78
	v_fmac_f32_e32 v77, v7, v79
	v_lshl_add_u32 v79, s60, 12, v152
	ds_write_b128 v79, v[80:83]
	ds_write_b128 v79, v[84:87] offset:16
	v_add_f32_dpp v77, v77, v77 quad_perm:[1,0,3,2] row_mask:0xf bank_mask:0xf bound_ctrl:1
	s_nop 1
	v_add_f32_dpp v77, v77, v77 quad_perm:[2,3,0,1] row_mask:0xf bank_mask:0xf bound_ctrl:1
	s_nop 1
	v_mov_b32_dpp v78, v77 row_half_mirror row_mask:0xf bank_mask:0xf bound_ctrl:1
	s_and_saveexec_b64 s[60:61], s[8:9]
	s_cbranch_execz .Lp_p0end
	v_add_f32_e32 v75, v75, v76
	v_mul_f32_e64 v74, v74, -v75
	v_mul_f32_e32 v75, v74, v72
	v_add_f32_e32 v78, v77, v78
	v_lshlrev_b32_e32 v74, 16, v48
	v_and_b32_e32 v76, 0xffff0000, v48
	v_mov_b32_e32 v77, v75
	ds_write_b128 v73, v[74:77] offset:1024
	v_lshlrev_b32_e32 v74, 16, v49
	v_and_b32_e32 v76, 0xffff0000, v49
	ds_write_b128 v73, v[74:77] offset:1040
	v_lshlrev_b32_e32 v74, 16, v50
	v_and_b32_e32 v76, 0xffff0000, v50
	s_and_b32 s69, s68, 0x70
	ds_write_b128 v73, v[74:77] offset:1056
	v_lshlrev_b32_e32 v74, 16, v51
	v_and_b32_e32 v76, 0xffff0000, v51
	v_lshl_add_u32 v72, s69, 2, v151
	ds_write_b128 v73, v[74:77] offset:1072
	ds_write_b32 v72, v78

; #define SCAN_BAR() do { asm volatile("s_waitcnt lgkmcnt(0)" ::: "memory"); __builtin_amdgcn_s_barrier(); asm volatile("" ::: "memory"); } while (0)
; __device__ __forceinline__ void scan_phase(const ScanArgs& s, char* shm) {
;     ...
;       for (int c = 0; c < NCH + 2; ++c) {
;         if ((c & 1) == par) { if (c + 2 < NCH) PROC(0, c + 2); }
;         else if (c + 1 < NCH) { PROC(1, c + 1); if (c + 3 < NCH) LOADRAW(c + 3); }
;         SCAN_BAR();
;       }
.Lp_join:
	s_add_i32 s67, s67, 1
	s_waitcnt lgkmcnt(0)
	s_barrier
	s_add_u32 s80, s80, 0x8000
	s_addc_u32 s81, s81, 0
	s_add_i32 s68, s68, 16
	s_cmp_lg_u32 s80, 0x2010000
	s_cbranch_scc1 .LBB0_143

; #define TILE_RC(t_, brow_, bcol_) do { const int wg_ = ((t_) & 7) * (nwg >> 3) + ((t_) >> 3); const int gid_ = wg_ / nig, fm_ = gid_ * 8, gsz_ = min(nM - fm_, 8); \
;     brow_ = (fm_ + ((wg_ % nig) % gsz_)) << 8; bcol_ = ((wg_ % nig) / gsz_) << 8; } while (0)
; __device__ __forceinline__ void gemm_run(const GemmDesc& g, char* shm) {
;     ...
;     for (int kt = 0; kt < nt; ++kt) {
;       const int cur = (b0 + kt) & 1;
;       asm volatile("s_waitcnt vmcnt(0)" ::: "memory");
;       __syncthreads();
;       if (kt + 1 < nt) { GLDS_STAGE(cur ^ 1, kt + 1); }
;       else if (t + (int)gridDim.x < nwg) {
;         int br, bc; TILE_RC(t + (int)gridDim.x, br, bc); SET_PTRS(br, bc); GLDS_STAGE(cur ^ 1, 0);
.LBB0_263:
	s_add_i32 s4, s49, s38
	s_add_i32 s4, s4, -1
	s_and_b32 s60, s4, 1
	s_cmp_ge_u32 s38, s23
	s_waitcnt vmcnt(0) lgkmcnt(0)
	s_barrier
	s_cbranch_scc0 .Lg_norm
	s_load_dword s4, s[72:73], 0x10
	s_load_dword s6, s[72:73], 0x0
	s_waitcnt lgkmcnt(0)
	s_lshr_b32 s4, s4, 16
	s_cmp_lg_u32 s4, 0
	s_cselect_b64 s[4:5], -1, 0
	s_cmp_lg_u64 s[4:5], 0
	s_addc_u32 s7, s6, s17
	s_cmp_lt_i32 s7, s85
	s_mov_b64 s[4:5], -1
	s_cbranch_scc1 .LBB0_266
	s_lshl_b32 s6, s60, 16
	s_mov_b64 s[4:5], 0
.LBB0_266:
	s_andn2_b64 vcc, exec, s[4:5]
	s_cbranch_vccnz .LBB0_284
	s_and_b32 s4, s7, 7
	s_mul_i32 s4, s4, s44
	s_ashr_i32 s5, s7, 3
	s_add_i32 s4, s4, s5
	s_abs_i32 s6, s4
	s_mul_hi_u32 s7, s6, s97
	s_mul_i32 s61, s7, s14
	s_sub_i32 s6, s6, s61
	s_ashr_i32 s5, s4, 31
	s_add_i32 s61, s7, 1
	s_sub_i32 s62, s6, s14
	s_cmp_ge_u32 s6, s14
	s_cselect_b32 s7, s61, s7
	s_cselect_b32 s6, s62, s6
	s_add_i32 s61, s7, 1
	s_cmp_ge_u32 s6, s14
	s_cselect_b32 s6, s61, s7
	s_xor_b32 s6, s6, s5
	s_sub_i32 s5, s6, s5
	s_lshl_b32 s6, s5, 3
	s_sub_i32 s7, 0x80, s6
	s_min_i32 s7, s7, 8
	s_abs_i32 s61, s7
	v_cvt_f32_u32_e32 v152, s61
	s_sub_i32 s63, 0, s61
	s_mul_i32 s5, s5, s14
	s_sub_i32 s4, s4, s5
	v_rcp_iflag_f32_e32 v152, v152
	s_abs_i32 s62, s4
	s_xor_b32 s5, s4, s7
	s_ashr_i32 s5, s5, 31
	v_mul_f32_e32 v152, 0x4f7ffffe, v152
	v_cvt_u32_f32_e32 v152, v152
	s_nop 0
	v_readfirstlane_b32 s68, v152
	s_mul_i32 s63, s63, s68
	s_mul_hi_u32 s63, s68, s63
	s_add_i32 s68, s68, s63
	s_mul_hi_u32 s63, s62, s68
	s_mul_i32 s68, s63, s61
	s_sub_i32 s62, s62, s68
	s_add_i32 s68, s63, 1
	s_sub_i32 s69, s62, s61
	s_cmp_ge_u32 s62, s61
	s_cselect_b32 s63, s68, s63
	s_cselect_b32 s62, s69, s62
	s_add_i32 s68, s63, 1
	s_cmp_ge_u32 s62, s61
	s_cselect_b32 s61, s68, s63
	s_xor_b32 s61, s61, s5
	s_sub_i32 s61, s61, s5
	s_mul_i32 s5, s61, s7
	s_sub_i32 s4, s4, s5
	s_add_i32 s4, s4, s6
	s_lshl_b32 s62, s4, 8
	v_add_u32_e32 v153, s62, v139
	v_mul_lo_u32 v152, v153, s84
	v_add_u32_e32 v154, v152, v136
	v_lshl_add_u32 v192, v154, 1, s15
	v_cndmask_b32_e64 v154, 0, 1, s[42:43]
	v_cmp_ne_u32_e64 s[4:5], 1, v154
	s_andn2_b64 vcc, exec, s[42:43]
	v_mov_b32_e32 v193, v192
	s_cbranch_vccnz .LBB0_271
	v_and_b32_e32 v153, 0x3fff, v153
	v_cmp_ne_u32_e32 vcc, 0, v153
	v_mov_b32_e32 v193, v176
	s_and_saveexec_b64 s[6:7], vcc
	v_add_u32_e32 v152, v152, v188
	v_lshl_add_u32 v193, v152, 1, s36
	s_or_b64 exec, exec, s[6:7]

; #define TILE_RC(t_, brow_, bcol_) do { const int wg_ = ((t_) & 7) * (nwg >> 3) + ((t_) >> 3); const int gid_ = wg_ / nig, fm_ = gid_ * 8, gsz_ = min(nM - fm_, 8); \
;     brow_ = (fm_ + ((wg_ % nig) % gsz_)) << 8; bcol_ = ((wg_ % nig) / gsz_) << 8; } while (0)
; #define LDA_(ks_, m_) (*(const bf16x8*)(SA(cur) + lds_byte2(wr * 128 + (m_) * 16 + fr, (ks_) * 32 + fq * 8)))
; #define LDB_(ks_, n_) (*(const bf16x8*)(SB(cur) + lds_byte2(wc * 64 + (n_) * 16 + fr, (ks_) * 32 + fq * 8)))
; __device__ __forceinline__ void gemm_run(const GemmDesc& g, char* shm) {
;     ...
;       if (kt + 1 < nt) { GLDS_STAGE(cur ^ 1, kt + 1); }
;       else if (t + (int)gridDim.x < nwg) {
;         int br, bc; TILE_RC(t + (int)gridDim.x, br, bc); SET_PTRS(br, bc); GLDS_STAGE(cur ^ 1, 0);
;       }
;       {
;     ...
;         bf16x8 Bf[2][4], Ar[3];
; #pragma unroll
;         for (int n = 0; n < 4; ++n) Bf[0][n] = LDB_(0, n);
;         Ar[0] = LDA_(0, 0); Ar[1] = LDA_(0, 1);
.LBB0_284:
	s_lshl_b32 s6, s60, 16
	v_mov_b32_e32 v152, s6
	v_add3_u32 v153, v152, v171, v170
	ds_read_b128 v[128:131], v153 offset:32768
	ds_read_b128 v[144:147], v153 offset:34816
	ds_read_b128 v[148:151], v153 offset:36864
	ds_read_b128 v[154:157], v153 offset:38912
	v_add3_u32 v232, v152, v171, v173
	v_add3_u32 v208, v152, v171, v174
	ds_read_b128 v[204:207], v232
	ds_read_b128 v[208:211], v208
	s_branch .Lg_comp
.Lg_norm:
	s_lshl_b32 s6, s60, 16
	v_mov_b32_e32 v152, s6
	v_add3_u32 v153, v152, v171, v170
	ds_read_b128 v[128:131], v153 offset:32768
	ds_read_b128 v[144:147], v153 offset:34816
	ds_read_b128 v[148:151], v153 offset:36864
	ds_read_b128 v[154:157], v153 offset:38912
	v_add3_u32 v232, v152, v171, v173
	v_add3_u32 v208, v152, v171, v174
	ds_read_b128 v[204:207], v232
	ds_read_b128 v[208:211], v208
	s_xor_b32 s4, s6, 0x10000
	v_readfirstlane_b32 s5, v137
	s_cmp_lt_u32 s38, s16
	s_cselect_b64 vcc, -1, 0
	s_add_i32 s4, s4, s5
	s_add_i32 s5, s39, s64
	s_add_i32 s7, s39, 0x80
	v_add_u32_e32 v239, s7, v192
	v_add_u32_e32 v240, s5, v193
	s_add_i32 m0, s4, 0x0
	v_cndmask_b32_e32 v239, v240, v239, vcc
	v_add_u32_e32 v241, s7, v202
	global_load_lds_dwordx4 v239, s[30:31]
	s_add_i32 m0, s4, 0x8000
	s_nop 0
	global_load_lds_dwordx4 v241, s[30:31]
	v_add_u32_e32 v239, s7, v194
	v_add_u32_e32 v240, s5, v196
	s_add_i32 m0, s4, 0x2000
	v_cndmask_b32_e32 v239, v240, v239, vcc
	v_add_u32_e32 v241, s7, v201
	global_load_lds_dwordx4 v239, s[30:31]
	s_add_i32 m0, s4, 0xa000
	s_nop 0
	global_load_lds_dwordx4 v241, s[30:31]
	v_add_u32_e32 v239, s7, v195
	v_add_u32_e32 v240, s5, v198
	s_add_i32 m0, s4, 0x4000
	v_cndmask_b32_e32 v239, v240, v239, vcc
	v_add_u32_e32 v241, s7, v200
	global_load_lds_dwordx4 v239, s[30:31]
	s_add_i32 m0, s4, 0xc000
	s_nop 0
	global_load_lds_dwordx4 v241, s[30:31]
	v_add_u32_e32 v239, s7, v197
	v_add_u32_e32 v240, s5, v199
	s_add_i32 m0, s4, 0x6000
	v_cndmask_b32_e32 v239, v240, v239, vcc
	v_add_u32_e32 v241, s7, v203
	global_load_lds_dwordx4 v239, s[30:31]
	s_add_i32 m0, s4, 0xe000
	s_nop 0
	global_load_lds_dwordx4 v241, s[30:31]
; #define LDA_(ks_, m_) (*(const bf16x8*)(SA(cur) + lds_byte2(wr * 128 + (m_) * 16 + fr, (ks_) * 32 + fq * 8)))
; #define LDB_(ks_, n_) (*(const bf16x8*)(SB(cur) + lds_byte2(wc * 64 + (n_) * 16 + fr, (ks_) * 32 + fq * 8)))
; __device__ __forceinline__ void gemm_run(const GemmDesc& g, char* shm) {
;     ...
;         __builtin_amdgcn_sched_barrier(0);
; #pragma unroll
;         for (int st = 0; st < 16; ++st) {
;           const int ks = st >> 3, m = st & 7;
;           if (st + 2 < 16) Ar[(st + 2) % 3] = LDA_((st + 2) >> 3, (st + 2) & 7);
;           if (st == 5) {
; #pragma unroll
;             for (int n = 0; n < 4; ++n) Bf[1][n] = LDB_(1, n);
;           }
; #pragma unroll
;           for (int n = 0; n < 4; ++n)
;             acc[m][n] = __builtin_amdgcn_mfma_f32_16x16x32_bf16(Bf[ks][n], Ar[st % 3], acc[m][n], 0, 0, 0);
;           __builtin_amdgcn_sched_barrier(0);
;         }
.Lg_comp:
	v_add3_u32 v233, v152, v181, v180
	s_waitcnt lgkmcnt(0)
	v_mfma_f32_16x16x32_bf16 v[124:127], v[128:131], v[204:207], v[124:127]
	ds_read_b128 v[212:215], v233
	v_mfma_f32_16x16x32_bf16 v[120:123], v[144:147], v[204:207], v[120:123]
	v_mfma_f32_16x16x32_bf16 v[116:119], v[148:151], v[204:207], v[116:119]
	v_mfma_f32_16x16x32_bf16 v[112:115], v[154:157], v[204:207], v[112:115]
	v_add3_u32 v234, v152, v181, v182
	v_mfma_f32_16x16x32_bf16 v[108:111], v[128:131], v[208:211], v[108:111]
	ds_read_b128 v[204:207], v234
	v_mfma_f32_16x16x32_bf16 v[104:107], v[144:147], v[208:211], v[104:107]
	v_mfma_f32_16x16x32_bf16 v[100:103], v[148:151], v[208:211], v[100:103]
	v_mfma_f32_16x16x32_bf16 v[96:99], v[154:157], v[208:211], v[96:99]
	v_add3_u32 v235, v152, v181, v183
	s_waitcnt lgkmcnt(0)
	v_mfma_f32_16x16x32_bf16 v[92:95], v[128:131], v[212:215], v[92:95]
	ds_read_b128 v[208:211], v235
	v_mfma_f32_16x16x32_bf16 v[88:91], v[144:147], v[212:215], v[88:91]
	v_mfma_f32_16x16x32_bf16 v[84:87], v[148:151], v[212:215], v[84:87]
	v_mfma_f32_16x16x32_bf16 v[80:83], v[154:157], v[212:215], v[80:83]
	v_add3_u32 v236, v152, v181, v184
	v_mfma_f32_16x16x32_bf16 v[76:79], v[128:131], v[204:207], v[76:79]
	ds_read_b128 v[212:215], v236
	v_mfma_f32_16x16x32_bf16 v[72:75], v[144:147], v[204:207], v[72:75]
	v_mfma_f32_16x16x32_bf16 v[68:71], v[148:151], v[204:207], v[68:71]
	v_mfma_f32_16x16x32_bf16 v[64:67], v[154:157], v[204:207], v[64:67]
	v_add3_u32 v237, v152, v181, v185
	s_waitcnt lgkmcnt(0)
	v_mfma_f32_16x16x32_bf16 v[60:63], v[128:131], v[208:211], v[60:63]
	ds_read_b128 v[204:207], v237
	v_mfma_f32_16x16x32_bf16 v[56:59], v[144:147], v[208:211], v[56:59]
	v_mfma_f32_16x16x32_bf16 v[52:55], v[148:151], v[208:211], v[52:55]
	v_mfma_f32_16x16x32_bf16 v[48:51], v[154:157], v[208:211], v[48:51]
	v_add3_u32 v238, v152, v181, v186
	ds_read_b128 v[208:211], v238
	ds_read_b128 v[216:219], v153 offset:33792
	ds_read_b128 v[220:223], v153 offset:35840
	ds_read_b128 v[224:227], v153 offset:37888
	ds_read_b128 v[228:231], v153 offset:39936
	v_mfma_f32_16x16x32_bf16 v[44:47], v[128:131], v[212:215], v[44:47]
	v_mfma_f32_16x16x32_bf16 v[40:43], v[144:147], v[212:215], v[40:43]
	v_mfma_f32_16x16x32_bf16 v[36:39], v[148:151], v[212:215], v[36:39]
	v_mfma_f32_16x16x32_bf16 v[32:35], v[154:157], v[212:215], v[32:35]
	s_waitcnt lgkmcnt(0)
	v_mfma_f32_16x16x32_bf16 v[28:31], v[128:131], v[204:207], v[28:31]
	ds_read_b128 v[212:215], v232 offset:1024
	v_mfma_f32_16x16x32_bf16 v[24:27], v[144:147], v[204:207], v[24:27]
	v_mfma_f32_16x16x32_bf16 v[20:23], v[148:151], v[204:207], v[20:23]
	v_mfma_f32_16x16x32_bf16 v[16:19], v[154:157], v[204:207], v[16:19]
	v_mfma_f32_16x16x32_bf16 v[12:15], v[128:131], v[208:211], v[12:15]
	v_add3_u32 v128, v152, v181, v174
	ds_read_b128 v[128:131], v128 offset:1024
	v_mfma_f32_16x16x32_bf16 v[8:11], v[144:147], v[208:211], v[8:11]
	v_mfma_f32_16x16x32_bf16 v[4:7], v[148:151], v[208:211], v[4:7]
	v_mfma_f32_16x16x32_bf16 v[0:3], v[154:157], v[208:211], v[0:3]
	s_waitcnt lgkmcnt(0)
	v_mfma_f32_16x16x32_bf16 v[124:127], v[216:219], v[212:215], v[124:127]
	ds_read_b128 v[144:147], v233 offset:1024
	v_mfma_f32_16x16x32_bf16 v[120:123], v[220:223], v[212:215], v[120:123]
	v_mfma_f32_16x16x32_bf16 v[116:119], v[224:227], v[212:215], v[116:119]
	v_mfma_f32_16x16x32_bf16 v[112:115], v[228:231], v[212:215], v[112:115]
	v_mfma_f32_16x16x32_bf16 v[108:111], v[216:219], v[128:131], v[108:111]
	ds_read_b128 v[148:151], v234 offset:1024
	v_mfma_f32_16x16x32_bf16 v[104:107], v[220:223], v[128:131], v[104:107]
	v_mfma_f32_16x16x32_bf16 v[100:103], v[224:227], v[128:131], v[100:103]
	v_mfma_f32_16x16x32_bf16 v[96:99], v[228:231], v[128:131], v[96:99]
	s_waitcnt lgkmcnt(0)
	v_mfma_f32_16x16x32_bf16 v[92:95], v[216:219], v[144:147], v[92:95]
	ds_read_b128 v[128:131], v235 offset:1024
	v_mfma_f32_16x16x32_bf16 v[88:91], v[220:223], v[144:147], v[88:91]
	v_mfma_f32_16x16x32_bf16 v[84:87], v[224:227], v[144:147], v[84:87]
	v_mfma_f32_16x16x32_bf16 v[80:83], v[228:231], v[144:147], v[80:83]
	v_mfma_f32_16x16x32_bf16 v[76:79], v[216:219], v[148:151], v[76:79]
	ds_read_b128 v[144:147], v236 offset:1024
	v_mfma_f32_16x16x32_bf16 v[72:75], v[220:223], v[148:151], v[72:75]
	v_mfma_f32_16x16x32_bf16 v[68:71], v[224:227], v[148:151], v[68:71]
	v_mfma_f32_16x16x32_bf16 v[64:67], v[228:231], v[148:151], v[64:67]
	s_waitcnt lgkmcnt(0)
	v_mfma_f32_16x16x32_bf16 v[60:63], v[216:219], v[128:131], v[60:63]
	ds_read_b128 v[148:151], v237 offset:1024
	v_mfma_f32_16x16x32_bf16 v[56:59], v[220:223], v[128:131], v[56:59]
	v_mfma_f32_16x16x32_bf16 v[52:55], v[224:227], v[128:131], v[52:55]
	v_mfma_f32_16x16x32_bf16 v[48:51], v[228:231], v[128:131], v[48:51]
	v_mfma_f32_16x16x32_bf16 v[44:47], v[216:219], v[144:147], v[44:47]
	ds_read_b128 v[128:131], v238 offset:1024
	v_mfma_f32_16x16x32_bf16 v[40:43], v[220:223], v[144:147], v[40:43]
	v_mfma_f32_16x16x32_bf16 v[36:39], v[224:227], v[144:147], v[36:39]
	v_mfma_f32_16x16x32_bf16 v[32:35], v[228:231], v[144:147], v[32:35]
	s_waitcnt lgkmcnt(0)
	v_mfma_f32_16x16x32_bf16 v[28:31], v[216:219], v[148:151], v[28:31]
	v_mfma_f32_16x16x32_bf16 v[24:27], v[220:223], v[148:151], v[24:27]
	v_mfma_f32_16x16x32_bf16 v[20:23], v[224:227], v[148:151], v[20:23]
	v_mfma_f32_16x16x32_bf16 v[16:19], v[228:231], v[148:151], v[16:19]
	v_mfma_f32_16x16x32_bf16 v[12:15], v[216:219], v[128:131], v[12:15]
	v_mfma_f32_16x16x32_bf16 v[8:11], v[220:223], v[128:131], v[8:11]
	v_mfma_f32_16x16x32_bf16 v[4:7], v[224:227], v[128:131], v[4:7]
	v_mfma_f32_16x16x32_bf16 v[0:3], v[228:231], v[128:131], v[0:3]
	s_add_i32 s38, s38, 1
	s_addk_i32 s39, 0x80
	s_cmp_eq_u32 s65, s39
	s_cbranch_scc0 .LBB0_263
